# phase 6 part 1 (merge prep A1) rewritten by hand with next-row loads double-buffered
# speedup vs baseline: 1.0058x; 1.0027x over previous
; DI float bflo(unsigned u) { return __uint_as_float(u << 16); }
; DI float bfhi(unsigned u) { return __uint_as_float(u & 0xffff0000u); }
; DI void phase_mergeprep(const P& p, int bid, int nb) {
;     ...
;     for (int row = bid * 8 + wid; row < T; row += nb * 8) {
;       const int c0 = lane * 16; const bf16_t* op = O + (size_t)row * 1024 + c0;
;       f32x4 v[4]; float ss = 0.f;
;       const bf16_t* ofp = (const bf16_t*)(p.ws + OFF_OFB) + (size_t)row * 1024 + c0; const bf16_t* obp = ofp + (size_t)T * 1024;
;       u32x4 f0 = *(const u32x4*)ofp, f1 = *(const u32x4*)(ofp + 8), b0 = *(const u32x4*)obp, b1 = *(const u32x4*)(obp + 8);
;       const u32x4 i0 = *(const u32x4*)op, i1 = *(const u32x4*)(op + 8);
; #pragma unroll
;       for (int q = 0; q < 4; ++q) { const unsigned ia = q < 2 ? i0[2 * (q & 1)] : i1[2 * (q & 1)], ib = q < 2 ? i0[2 * (q & 1) + 1] : i1[2 * (q & 1) + 1];
;         v[q] = (f32x4){bflo(ia), bfhi(ia), bflo(ib), bfhi(ib)};
;         const unsigned fa = q < 2 ? f0[2 * (q & 1)] : f1[2 * (q & 1)], fb = q < 2 ? f0[2 * (q & 1) + 1] : f1[2 * (q & 1) + 1];
;         const unsigned ba = q < 2 ? b0[2 * (q & 1)] : b1[2 * (q & 1)], bb = q < 2 ? b0[2 * (q & 1) + 1] : b1[2 * (q & 1) + 1];
;         v[q].x += bflo(fa) + bflo(ba); v[q].y += bfhi(fa) + bfhi(ba); v[q].z += bflo(fb) + bflo(bb); v[q].w += bfhi(fb) + bfhi(bb);
;         ss += v[q].x * v[q].x + v[q].y * v[q].y + v[q].z * v[q].z + v[q].w * v[q].w; }
;       ss += __shfl_xor(ss, 1, 64); ss += __shfl_xor(ss, 2, 64); ss += __shfl_xor(ss, 4, 64); ss += __shfl_xor(ss, 8, 64);
;       const float rstd = rsqrtf(ss * (1.f / 256.f) + 1e-6f);
;       const bf16_t* gp = G + (size_t)row * 1024 + c0; u32x4 g0 = *(const u32x4*)gp, g1 = *(const u32x4*)(gp + 8);
;       const float* nw = p.gla_norm + (c0 & 255);
;       float gv[16];
; #pragma unroll
;       for (int e = 0; e < 4; ++e) { gv[2 * e] = bflo(g0[e]); gv[2 * e + 1] = bfhi(g0[e]); gv[8 + 2 * e] = bflo(g1[e]); gv[8 + 2 * e + 1] = bfhi(g1[e]); }
;       float y[16];
; #pragma unroll
;       for (int e = 0; e < 16; ++e) y[e] = v[e >> 2][e & 3] * rstd * nw[e] * gv[e];
.LBB0_508:
	s_waitcnt vmcnt(0)
	v_lshrrev_b32_e32 v4, 6, v29
	s_lshl_b32 s0, s2, 3
	v_add_u32_e32 v5, s0, v4
	v_and_b32_e32 v3, 63, v29
	v_lshlrev_b32_e32 v2, 5, v3
	v_readfirstlane_b32 s3, v5
	v_and_b32_e32 v6, 15, v3
	v_lshlrev_b32_e32 v6, 6, v6
	v_xor_b32_e32 v8, 1, v3
	v_lshlrev_b32_e32 v8, 2, v8
	v_xor_b32_e32 v9, 2, v3
	v_lshlrev_b32_e32 v9, 2, v9
	v_xor_b32_e32 v10, 4, v3
	v_lshlrev_b32_e32 v10, 2, v10
	v_xor_b32_e32 v11, 8, v3
	v_lshlrev_b32_e32 v11, 2, v11
	s_lshl_b32 s6, s88, 3
	s_mov_b32 s7, 0x8000
	s_cmp_ge_i32 s3, s7
	s_cbranch_scc1 .Lma_done
	v_readlane_b32 s26, v254, 30
	v_readlane_b32 s27, v254, 31
	s_nop 3
	global_load_dwordx4 v[16:19], v6, s[26:27]
	global_load_dwordx4 v[20:23], v6, s[26:27] offset:16
	global_load_dwordx4 v[24:27], v6, s[26:27] offset:32
	global_load_dwordx4 v[28:31], v6, s[26:27] offset:48
	s_lshl_b32 s10, s3, 11
	s_add_u32 s12, s84, s10
	s_addc_u32 s13, s85, 0
	s_add_u32 s14, s12, 0x2bd00000
	s_addc_u32 s15, s13, 0
	s_add_u32 s16, s12, 0xbb00000
	s_addc_u32 s17, s13, 0
	s_add_u32 s18, s12, 0xfb00000
	s_addc_u32 s19, s13, 0
	s_add_u32 s20, s12, 0x1bd00000
	s_addc_u32 s21, s13, 0
	global_load_dwordx4 v[32:35], v2, s[14:15]
	global_load_dwordx4 v[36:39], v2, s[14:15] offset:16
	global_load_dwordx4 v[40:43], v2, s[16:17]
	global_load_dwordx4 v[44:47], v2, s[16:17] offset:16
	global_load_dwordx4 v[48:51], v2, s[18:19]
	global_load_dwordx4 v[52:55], v2, s[18:19] offset:16
	global_load_dwordx4 v[56:59], v2, s[20:21]
	global_load_dwordx4 v[60:63], v2, s[20:21] offset:16
.Lma_half_A:
	s_add_i32 s23, s3, s6
	s_cmp_lt_i32 s23, s7
	s_cselect_b32 s22, 1, 0
	s_cselect_b32 s0, s23, s3
	s_lshl_b32 s10, s3, 12
	s_add_u32 s24, s84, s10
	s_addc_u32 s25, s85, 0
	s_add_u32 s24, s24, 0x1000000
	s_addc_u32 s25, s25, 0
	s_lshl_b32 s10, s0, 11
	s_add_u32 s12, s84, s10
	s_addc_u32 s13, s85, 0
	s_add_u32 s14, s12, 0x2bd00000
	s_addc_u32 s15, s13, 0
	s_add_u32 s16, s12, 0xbb00000
	s_addc_u32 s17, s13, 0
	s_add_u32 s18, s12, 0xfb00000
	s_addc_u32 s19, s13, 0
	s_add_u32 s20, s12, 0x1bd00000
	s_addc_u32 s21, s13, 0
	global_load_dwordx4 v[64:67], v2, s[14:15]
	global_load_dwordx4 v[68:71], v2, s[14:15] offset:16
	global_load_dwordx4 v[72:75], v2, s[16:17]
	global_load_dwordx4 v[76:79], v2, s[16:17] offset:16
	global_load_dwordx4 v[80:83], v2, s[18:19]
	global_load_dwordx4 v[84:87], v2, s[18:19] offset:16
	global_load_dwordx4 v[88:91], v2, s[20:21]
	global_load_dwordx4 v[92:95], v2, s[20:21] offset:16
	s_waitcnt vmcnt(8)
	v_lshlrev_b32_e32 v144, 16, v40
	v_lshlrev_b32_e32 v145, 16, v48
	v_and_b32_e32 v146, 0xffff0000, v40
	v_and_b32_e32 v147, 0xffff0000, v48
	v_add_f32_e32 v144, v144, v145
	v_add_f32_e32 v146, v146, v147
	v_lshlrev_b32_e32 v96, 16, v32
	v_and_b32_e32 v97, 0xffff0000, v32
	v_add_f32_e32 v96, v96, v144
	v_add_f32_e32 v97, v97, v146
	v_lshlrev_b32_e32 v144, 16, v41
	v_lshlrev_b32_e32 v145, 16, v49
	v_and_b32_e32 v146, 0xffff0000, v41
	v_and_b32_e32 v147, 0xffff0000, v49
	v_add_f32_e32 v144, v144, v145
	v_add_f32_e32 v146, v146, v147
	v_lshlrev_b32_e32 v98, 16, v33
	v_and_b32_e32 v99, 0xffff0000, v33
	v_add_f32_e32 v98, v98, v144
	v_add_f32_e32 v99, v99, v146
	v_lshlrev_b32_e32 v144, 16, v42
	v_lshlrev_b32_e32 v145, 16, v50
	v_and_b32_e32 v146, 0xffff0000, v42
	v_and_b32_e32 v147, 0xffff0000, v50
	v_add_f32_e32 v144, v144, v145
	v_add_f32_e32 v146, v146, v147
	v_lshlrev_b32_e32 v100, 16, v34
	v_and_b32_e32 v101, 0xffff0000, v34
	v_add_f32_e32 v100, v100, v144
	v_add_f32_e32 v101, v101, v146
	v_lshlrev_b32_e32 v144, 16, v43
	v_lshlrev_b32_e32 v145, 16, v51
	v_and_b32_e32 v146, 0xffff0000, v43
	v_and_b32_e32 v147, 0xffff0000, v51
	v_add_f32_e32 v144, v144, v145
	v_add_f32_e32 v146, v146, v147
	v_lshlrev_b32_e32 v102, 16, v35
	v_and_b32_e32 v103, 0xffff0000, v35
	v_add_f32_e32 v102, v102, v144
	v_add_f32_e32 v103, v103, v146
	v_lshlrev_b32_e32 v144, 16, v44
	v_lshlrev_b32_e32 v145, 16, v52
	v_and_b32_e32 v146, 0xffff0000, v44
	v_and_b32_e32 v147, 0xffff0000, v52
	v_add_f32_e32 v144, v144, v145
	v_add_f32_e32 v146, v146, v147
	v_lshlrev_b32_e32 v104, 16, v36
	v_and_b32_e32 v105, 0xffff0000, v36
	v_add_f32_e32 v104, v104, v144
	v_add_f32_e32 v105, v105, v146
	v_lshlrev_b32_e32 v144, 16, v45
	v_lshlrev_b32_e32 v145, 16, v53
	v_and_b32_e32 v146, 0xffff0000, v45
	v_and_b32_e32 v147, 0xffff0000, v53
	v_add_f32_e32 v144, v144, v145
	v_add_f32_e32 v146, v146, v147
	v_lshlrev_b32_e32 v106, 16, v37
	v_and_b32_e32 v107, 0xffff0000, v37
	v_add_f32_e32 v106, v106, v144
	v_add_f32_e32 v107, v107, v146
	v_lshlrev_b32_e32 v144, 16, v46
	v_lshlrev_b32_e32 v145, 16, v54
	v_and_b32_e32 v146, 0xffff0000, v46
	v_and_b32_e32 v147, 0xffff0000, v54
	v_add_f32_e32 v144, v144, v145
	v_add_f32_e32 v146, v146, v147
	v_lshlrev_b32_e32 v108, 16, v38
	v_and_b32_e32 v109, 0xffff0000, v38
	v_add_f32_e32 v108, v108, v144
	v_add_f32_e32 v109, v109, v146
	v_lshlrev_b32_e32 v144, 16, v47
	v_lshlrev_b32_e32 v145, 16, v55
	v_and_b32_e32 v146, 0xffff0000, v47
	v_and_b32_e32 v147, 0xffff0000, v55
	v_add_f32_e32 v144, v144, v145
	v_add_f32_e32 v146, v146, v147
	v_lshlrev_b32_e32 v110, 16, v39
	v_and_b32_e32 v111, 0xffff0000, v39
	v_add_f32_e32 v110, v110, v144
	v_add_f32_e32 v111, v111, v146
	v_mul_f32_e32 v136, v96, v96
	v_fmac_f32_e32 v136, v97, v97
	v_fmac_f32_e32 v136, v98, v98
	v_fmac_f32_e32 v136, v99, v99
	v_mul_f32_e32 v137, v100, v100
	v_fmac_f32_e32 v137, v101, v101
	v_fmac_f32_e32 v137, v102, v102
	v_fmac_f32_e32 v137, v103, v103
	v_mul_f32_e32 v138, v104, v104
	v_fmac_f32_e32 v138, v105, v105
	v_fmac_f32_e32 v138, v106, v106
	v_fmac_f32_e32 v138, v107, v107
	v_mul_f32_e32 v139, v108, v108
	v_fmac_f32_e32 v139, v109, v109
	v_fmac_f32_e32 v139, v110, v110
	v_fmac_f32_e32 v139, v111, v111
	v_add_f32_e32 v136, v136, v137
	v_add_f32_e32 v138, v138, v139
	v_add_f32_e32 v136, v136, v138
	ds_bpermute_b32 v140, v8, v136
	v_lshlrev_b32_e32 v112, 16, v56
	v_and_b32_e32 v113, 0xffff0000, v56
	v_lshlrev_b32_e32 v114, 16, v57
	v_and_b32_e32 v115, 0xffff0000, v57
	s_waitcnt lgkmcnt(0)
; DI float bflo(unsigned u) { return __uint_as_float(u << 16); }
; DI void phase_mergeprep(const P& p, int bid, int nb) {
;     ...
;     for (int row = bid * 8 + wid; row < T; row += nb * 8) {
;       const int c0 = lane * 16; const bf16_t* op = O + (size_t)row * 1024 + c0;
;       f32x4 v[4]; float ss = 0.f;
;       const bf16_t* ofp = (const bf16_t*)(p.ws + OFF_OFB) + (size_t)row * 1024 + c0; const bf16_t* obp = ofp + (size_t)T * 1024;
;       u32x4 f0 = *(const u32x4*)ofp, f1 = *(const u32x4*)(ofp + 8), b0 = *(const u32x4*)obp, b1 = *(const u32x4*)(obp + 8);
;       const u32x4 i0 = *(const u32x4*)op, i1 = *(const u32x4*)(op + 8);
; #pragma unroll
;       for (int q = 0; q < 4; ++q) { const unsigned ia = q < 2 ? i0[2 * (q & 1)] : i1[2 * (q & 1)], ib = q < 2 ? i0[2 * (q & 1) + 1] : i1[2 * (q & 1) + 1];
;         v[q] = (f32x4){bflo(ia), bfhi(ia), bflo(ib), bfhi(ib)};
;         const unsigned fa = q < 2 ? f0[2 * (q & 1)] : f1[2 * (q & 1)], fb = q < 2 ? f0[2 * (q & 1) + 1] : f1[2 * (q & 1) + 1];
;         const unsigned ba = q < 2 ? b0[2 * (q & 1)] : b1[2 * (q & 1)], bb = q < 2 ? b0[2 * (q & 1) + 1] : b1[2 * (q & 1) + 1];
;         v[q].x += bflo(fa) + bflo(ba); v[q].y += bfhi(fa) + bfhi(ba); v[q].z += bflo(fb) + bflo(bb); v[q].w += bfhi(fb) + bfhi(bb);
;         ss += v[q].x * v[q].x + v[q].y * v[q].y + v[q].z * v[q].z + v[q].w * v[q].w; }
;       ss += __shfl_xor(ss, 1, 64); ss += __shfl_xor(ss, 2, 64); ss += __shfl_xor(ss, 4, 64); ss += __shfl_xor(ss, 8, 64);
;       const float rstd = rsqrtf(ss * (1.f / 256.f) + 1e-6f);
;       const bf16_t* gp = G + (size_t)row * 1024 + c0; u32x4 g0 = *(const u32x4*)gp, g1 = *(const u32x4*)(gp + 8);
;       const float* nw = p.gla_norm + (c0 & 255);
;       float gv[16];
; #pragma unroll
;       for (int e = 0; e < 4; ++e) { gv[2 * e] = bflo(g0[e]); gv[2 * e + 1] = bfhi(g0[e]); gv[8 + 2 * e] = bflo(g1[e]); gv[8 + 2 * e + 1] = bfhi(g1[e]); }
;       float y[16];
; #pragma unroll
;       for (int e = 0; e < 16; ++e) y[e] = v[e >> 2][e & 3] * rstd * nw[e] * gv[e];
;       u32x4 w0, w1;
;       w0.x = pk2(y[0], y[1]); w0.y = pk2(y[2], y[3]); w0.z = pk2(y[4], y[5]); w0.w = pk2(y[6], y[7]);
;       w1.x = pk2(y[8], y[9]); w1.y = pk2(y[10], y[11]); w1.z = pk2(y[12], y[13]); w1.w = pk2(y[14], y[15]);
;       bf16_t* ap = AM + (size_t)row * 2048 + c0; *(u32x4*)ap = w0; *(u32x4*)(ap + 8) = w1;
	v_add_f32_e32 v136, v136, v140
	ds_bpermute_b32 v140, v9, v136
	v_lshlrev_b32_e32 v116, 16, v58
	v_and_b32_e32 v117, 0xffff0000, v58
	v_lshlrev_b32_e32 v118, 16, v59
	v_and_b32_e32 v119, 0xffff0000, v59
	s_waitcnt lgkmcnt(0)
	v_add_f32_e32 v136, v136, v140
	ds_bpermute_b32 v140, v10, v136
	v_lshlrev_b32_e32 v120, 16, v60
	v_and_b32_e32 v121, 0xffff0000, v60
	v_lshlrev_b32_e32 v122, 16, v61
	v_and_b32_e32 v123, 0xffff0000, v61
	s_waitcnt lgkmcnt(0)
	v_add_f32_e32 v136, v136, v140
	ds_bpermute_b32 v140, v11, v136
	v_lshlrev_b32_e32 v124, 16, v62
	v_and_b32_e32 v125, 0xffff0000, v62
	v_lshlrev_b32_e32 v126, 16, v63
	v_and_b32_e32 v127, 0xffff0000, v63
	s_waitcnt lgkmcnt(0)
	v_add_f32_e32 v136, v136, v140
	v_mov_b32_e32 v140, 0x358637bd
	v_fmac_f32_e32 v140, 0x3b800000, v136
	v_rsq_f32_e32 v142, v140
	s_nop 0
	v_pk_mul_f32 v[96:97], v[142:143], v[96:97] op_sel_hi:[0,1]
	v_pk_mul_f32 v[96:97], v[96:97], v[16:17]
	v_pk_mul_f32 v[96:97], v[96:97], v[112:113]
	v_cvt_pk_bf16_f32 v128, v96, v97
	v_pk_mul_f32 v[98:99], v[142:143], v[98:99] op_sel_hi:[0,1]
	v_pk_mul_f32 v[98:99], v[98:99], v[18:19]
	v_pk_mul_f32 v[98:99], v[98:99], v[114:115]
	v_cvt_pk_bf16_f32 v129, v98, v99
	v_pk_mul_f32 v[100:101], v[142:143], v[100:101] op_sel_hi:[0,1]
	v_pk_mul_f32 v[100:101], v[100:101], v[20:21]
	v_pk_mul_f32 v[100:101], v[100:101], v[116:117]
	v_cvt_pk_bf16_f32 v130, v100, v101
	v_pk_mul_f32 v[102:103], v[142:143], v[102:103] op_sel_hi:[0,1]
	v_pk_mul_f32 v[102:103], v[102:103], v[22:23]
	v_pk_mul_f32 v[102:103], v[102:103], v[118:119]
	v_cvt_pk_bf16_f32 v131, v102, v103
	v_pk_mul_f32 v[104:105], v[142:143], v[104:105] op_sel_hi:[0,1]
	v_pk_mul_f32 v[104:105], v[104:105], v[24:25]
	v_pk_mul_f32 v[104:105], v[104:105], v[120:121]
	v_cvt_pk_bf16_f32 v132, v104, v105
	v_pk_mul_f32 v[106:107], v[142:143], v[106:107] op_sel_hi:[0,1]
	v_pk_mul_f32 v[106:107], v[106:107], v[26:27]
	v_pk_mul_f32 v[106:107], v[106:107], v[122:123]
	v_cvt_pk_bf16_f32 v133, v106, v107
	v_pk_mul_f32 v[108:109], v[142:143], v[108:109] op_sel_hi:[0,1]
	v_pk_mul_f32 v[108:109], v[108:109], v[28:29]
	v_pk_mul_f32 v[108:109], v[108:109], v[124:125]
	v_cvt_pk_bf16_f32 v134, v108, v109
	v_pk_mul_f32 v[110:111], v[142:143], v[110:111] op_sel_hi:[0,1]
	v_pk_mul_f32 v[110:111], v[110:111], v[30:31]
	v_pk_mul_f32 v[110:111], v[110:111], v[126:127]
	v_cvt_pk_bf16_f32 v135, v110, v111
	global_store_dwordx4 v2, v[128:131], s[24:25]
	global_store_dwordx4 v2, v[132:135], s[24:25] offset:16
	s_cmp_eq_u32 s22, 0
	s_cbranch_scc1 .Lma_done
	s_mov_b32 s3, s23
.Lma_half_B:
	s_add_i32 s23, s3, s6
	s_cmp_lt_i32 s23, s7
	s_cselect_b32 s22, 1, 0
	s_cselect_b32 s0, s23, s3
	s_lshl_b32 s10, s3, 12
	s_add_u32 s24, s84, s10
	s_addc_u32 s25, s85, 0
	s_add_u32 s24, s24, 0x1000000
	s_addc_u32 s25, s25, 0
	s_lshl_b32 s10, s0, 11
	s_add_u32 s12, s84, s10
	s_addc_u32 s13, s85, 0
	s_add_u32 s14, s12, 0x2bd00000
	s_addc_u32 s15, s13, 0
	s_add_u32 s16, s12, 0xbb00000
	s_addc_u32 s17, s13, 0
	s_add_u32 s18, s12, 0xfb00000
	s_addc_u32 s19, s13, 0
	s_add_u32 s20, s12, 0x1bd00000
	s_addc_u32 s21, s13, 0
	global_load_dwordx4 v[32:35], v2, s[14:15]
	global_load_dwordx4 v[36:39], v2, s[14:15] offset:16
	global_load_dwordx4 v[40:43], v2, s[16:17]
	global_load_dwordx4 v[44:47], v2, s[16:17] offset:16
	global_load_dwordx4 v[48:51], v2, s[18:19]
	global_load_dwordx4 v[52:55], v2, s[18:19] offset:16
	global_load_dwordx4 v[56:59], v2, s[20:21]
	global_load_dwordx4 v[60:63], v2, s[20:21] offset:16
	s_waitcnt vmcnt(8)
	v_lshlrev_b32_e32 v144, 16, v72
	v_lshlrev_b32_e32 v145, 16, v80
	v_and_b32_e32 v146, 0xffff0000, v72
	v_and_b32_e32 v147, 0xffff0000, v80
	v_add_f32_e32 v144, v144, v145
	v_add_f32_e32 v146, v146, v147
	v_lshlrev_b32_e32 v96, 16, v64
	v_and_b32_e32 v97, 0xffff0000, v64
	v_add_f32_e32 v96, v96, v144
	v_add_f32_e32 v97, v97, v146
	v_lshlrev_b32_e32 v144, 16, v73
	v_lshlrev_b32_e32 v145, 16, v81
	v_and_b32_e32 v146, 0xffff0000, v73
	v_and_b32_e32 v147, 0xffff0000, v81
	v_add_f32_e32 v144, v144, v145
	v_add_f32_e32 v146, v146, v147
	v_lshlrev_b32_e32 v98, 16, v65
	v_and_b32_e32 v99, 0xffff0000, v65
	v_add_f32_e32 v98, v98, v144
	v_add_f32_e32 v99, v99, v146
	v_lshlrev_b32_e32 v144, 16, v74
	v_lshlrev_b32_e32 v145, 16, v82
	v_and_b32_e32 v146, 0xffff0000, v74
	v_and_b32_e32 v147, 0xffff0000, v82
	v_add_f32_e32 v144, v144, v145
	v_add_f32_e32 v146, v146, v147
	v_lshlrev_b32_e32 v100, 16, v66
	v_and_b32_e32 v101, 0xffff0000, v66
	v_add_f32_e32 v100, v100, v144
	v_add_f32_e32 v101, v101, v146
	v_lshlrev_b32_e32 v144, 16, v75
	v_lshlrev_b32_e32 v145, 16, v83
	v_and_b32_e32 v146, 0xffff0000, v75
	v_and_b32_e32 v147, 0xffff0000, v83
	v_add_f32_e32 v144, v144, v145
	v_add_f32_e32 v146, v146, v147
	v_lshlrev_b32_e32 v102, 16, v67
	v_and_b32_e32 v103, 0xffff0000, v67
	v_add_f32_e32 v102, v102, v144
	v_add_f32_e32 v103, v103, v146
	v_lshlrev_b32_e32 v144, 16, v76
	v_lshlrev_b32_e32 v145, 16, v84
	v_and_b32_e32 v146, 0xffff0000, v76
	v_and_b32_e32 v147, 0xffff0000, v84
	v_add_f32_e32 v144, v144, v145
	v_add_f32_e32 v146, v146, v147
	v_lshlrev_b32_e32 v104, 16, v68
	v_and_b32_e32 v105, 0xffff0000, v68
	v_add_f32_e32 v104, v104, v144
	v_add_f32_e32 v105, v105, v146
	v_lshlrev_b32_e32 v144, 16, v77
	v_lshlrev_b32_e32 v145, 16, v85
	v_and_b32_e32 v146, 0xffff0000, v77
	v_and_b32_e32 v147, 0xffff0000, v85
	v_add_f32_e32 v144, v144, v145
	v_add_f32_e32 v146, v146, v147
	v_lshlrev_b32_e32 v106, 16, v69
	v_and_b32_e32 v107, 0xffff0000, v69
	v_add_f32_e32 v106, v106, v144
	v_add_f32_e32 v107, v107, v146
	v_lshlrev_b32_e32 v144, 16, v78
	v_lshlrev_b32_e32 v145, 16, v86
	v_and_b32_e32 v146, 0xffff0000, v78
	v_and_b32_e32 v147, 0xffff0000, v86
	v_add_f32_e32 v144, v144, v145
	v_add_f32_e32 v146, v146, v147
	v_lshlrev_b32_e32 v108, 16, v70
	v_and_b32_e32 v109, 0xffff0000, v70
	v_add_f32_e32 v108, v108, v144
	v_add_f32_e32 v109, v109, v146
	v_lshlrev_b32_e32 v144, 16, v79
	v_lshlrev_b32_e32 v145, 16, v87
	v_and_b32_e32 v146, 0xffff0000, v79
	v_and_b32_e32 v147, 0xffff0000, v87
	v_add_f32_e32 v144, v144, v145
	v_add_f32_e32 v146, v146, v147
	v_lshlrev_b32_e32 v110, 16, v71
	v_and_b32_e32 v111, 0xffff0000, v71
	v_add_f32_e32 v110, v110, v144
	v_add_f32_e32 v111, v111, v146
	v_mul_f32_e32 v136, v96, v96
	v_fmac_f32_e32 v136, v97, v97
	v_fmac_f32_e32 v136, v98, v98
	v_fmac_f32_e32 v136, v99, v99
	v_mul_f32_e32 v137, v100, v100
	v_fmac_f32_e32 v137, v101, v101
	v_fmac_f32_e32 v137, v102, v102
	v_fmac_f32_e32 v137, v103, v103
	v_mul_f32_e32 v138, v104, v104
	v_fmac_f32_e32 v138, v105, v105
	v_fmac_f32_e32 v138, v106, v106
	v_fmac_f32_e32 v138, v107, v107
	v_mul_f32_e32 v139, v108, v108
	v_fmac_f32_e32 v139, v109, v109
	v_fmac_f32_e32 v139, v110, v110
	v_fmac_f32_e32 v139, v111, v111
	v_add_f32_e32 v136, v136, v137
	v_add_f32_e32 v138, v138, v139
	v_add_f32_e32 v136, v136, v138
	ds_bpermute_b32 v140, v8, v136
	v_lshlrev_b32_e32 v112, 16, v88
	v_and_b32_e32 v113, 0xffff0000, v88
	v_lshlrev_b32_e32 v114, 16, v89
	v_and_b32_e32 v115, 0xffff0000, v89
	s_waitcnt lgkmcnt(0)
; DI void phase_mergeprep(const P& p, int bid, int nb) {
;     ...
;     for (int row = bid * 8 + wid; row < T; row += nb * 8) {
;       const int c0 = lane * 16; const bf16_t* op = O + (size_t)row * 1024 + c0;
;       f32x4 v[4]; float ss = 0.f;
;       const bf16_t* ofp = (const bf16_t*)(p.ws + OFF_OFB) + (size_t)row * 1024 + c0; const bf16_t* obp = ofp + (size_t)T * 1024;
;       u32x4 f0 = *(const u32x4*)ofp, f1 = *(const u32x4*)(ofp + 8), b0 = *(const u32x4*)obp, b1 = *(const u32x4*)(obp + 8);
;       const u32x4 i0 = *(const u32x4*)op, i1 = *(const u32x4*)(op + 8);
; #pragma unroll
;       for (int q = 0; q < 4; ++q) { const unsigned ia = q < 2 ? i0[2 * (q & 1)] : i1[2 * (q & 1)], ib = q < 2 ? i0[2 * (q & 1) + 1] : i1[2 * (q & 1) + 1];
;         v[q] = (f32x4){bflo(ia), bfhi(ia), bflo(ib), bfhi(ib)};
;         const unsigned fa = q < 2 ? f0[2 * (q & 1)] : f1[2 * (q & 1)], fb = q < 2 ? f0[2 * (q & 1) + 1] : f1[2 * (q & 1) + 1];
;         const unsigned ba = q < 2 ? b0[2 * (q & 1)] : b1[2 * (q & 1)], bb = q < 2 ? b0[2 * (q & 1) + 1] : b1[2 * (q & 1) + 1];
;         v[q].x += bflo(fa) + bflo(ba); v[q].y += bfhi(fa) + bfhi(ba); v[q].z += bflo(fb) + bflo(bb); v[q].w += bfhi(fb) + bfhi(bb);
;         ss += v[q].x * v[q].x + v[q].y * v[q].y + v[q].z * v[q].z + v[q].w * v[q].w; }
;       ss += __shfl_xor(ss, 1, 64); ss += __shfl_xor(ss, 2, 64); ss += __shfl_xor(ss, 4, 64); ss += __shfl_xor(ss, 8, 64);
;       const float rstd = rsqrtf(ss * (1.f / 256.f) + 1e-6f);
;       const bf16_t* gp = G + (size_t)row * 1024 + c0; u32x4 g0 = *(const u32x4*)gp, g1 = *(const u32x4*)(gp + 8);
;       const float* nw = p.gla_norm + (c0 & 255);
;       float gv[16];
; #pragma unroll
;       for (int e = 0; e < 4; ++e) { gv[2 * e] = bflo(g0[e]); gv[2 * e + 1] = bfhi(g0[e]); gv[8 + 2 * e] = bflo(g1[e]); gv[8 + 2 * e + 1] = bfhi(g1[e]); }
;       float y[16];
; #pragma unroll
;       for (int e = 0; e < 16; ++e) y[e] = v[e >> 2][e & 3] * rstd * nw[e] * gv[e];
;       u32x4 w0, w1;
;       w0.x = pk2(y[0], y[1]); w0.y = pk2(y[2], y[3]); w0.z = pk2(y[4], y[5]); w0.w = pk2(y[6], y[7]);
;       w1.x = pk2(y[8], y[9]); w1.y = pk2(y[10], y[11]); w1.z = pk2(y[12], y[13]); w1.w = pk2(y[14], y[15]);
;       bf16_t* ap = AM + (size_t)row * 2048 + c0; *(u32x4*)ap = w0; *(u32x4*)(ap + 8) = w1;
;     ...
;     for (int it = bid; it < 4096; it += nb) {
	v_add_f32_e32 v136, v136, v140
	ds_bpermute_b32 v140, v9, v136
	v_lshlrev_b32_e32 v116, 16, v90
	v_and_b32_e32 v117, 0xffff0000, v90
	v_lshlrev_b32_e32 v118, 16, v91
	v_and_b32_e32 v119, 0xffff0000, v91
	s_waitcnt lgkmcnt(0)
	v_add_f32_e32 v136, v136, v140
	ds_bpermute_b32 v140, v10, v136
	v_lshlrev_b32_e32 v120, 16, v92
	v_and_b32_e32 v121, 0xffff0000, v92
	v_lshlrev_b32_e32 v122, 16, v93
	v_and_b32_e32 v123, 0xffff0000, v93
	s_waitcnt lgkmcnt(0)
	v_add_f32_e32 v136, v136, v140
	ds_bpermute_b32 v140, v11, v136
	v_lshlrev_b32_e32 v124, 16, v94
	v_and_b32_e32 v125, 0xffff0000, v94
	v_lshlrev_b32_e32 v126, 16, v95
	v_and_b32_e32 v127, 0xffff0000, v95
	s_waitcnt lgkmcnt(0)
	v_add_f32_e32 v136, v136, v140
	v_mov_b32_e32 v140, 0x358637bd
	v_fmac_f32_e32 v140, 0x3b800000, v136
	v_rsq_f32_e32 v142, v140
	s_nop 0
	v_pk_mul_f32 v[96:97], v[142:143], v[96:97] op_sel_hi:[0,1]
	v_pk_mul_f32 v[96:97], v[96:97], v[16:17]
	v_pk_mul_f32 v[96:97], v[96:97], v[112:113]
	v_cvt_pk_bf16_f32 v128, v96, v97
	v_pk_mul_f32 v[98:99], v[142:143], v[98:99] op_sel_hi:[0,1]
	v_pk_mul_f32 v[98:99], v[98:99], v[18:19]
	v_pk_mul_f32 v[98:99], v[98:99], v[114:115]
	v_cvt_pk_bf16_f32 v129, v98, v99
	v_pk_mul_f32 v[100:101], v[142:143], v[100:101] op_sel_hi:[0,1]
	v_pk_mul_f32 v[100:101], v[100:101], v[20:21]
	v_pk_mul_f32 v[100:101], v[100:101], v[116:117]
	v_cvt_pk_bf16_f32 v130, v100, v101
	v_pk_mul_f32 v[102:103], v[142:143], v[102:103] op_sel_hi:[0,1]
	v_pk_mul_f32 v[102:103], v[102:103], v[22:23]
	v_pk_mul_f32 v[102:103], v[102:103], v[118:119]
	v_cvt_pk_bf16_f32 v131, v102, v103
	v_pk_mul_f32 v[104:105], v[142:143], v[104:105] op_sel_hi:[0,1]
	v_pk_mul_f32 v[104:105], v[104:105], v[24:25]
	v_pk_mul_f32 v[104:105], v[104:105], v[120:121]
	v_cvt_pk_bf16_f32 v132, v104, v105
	v_pk_mul_f32 v[106:107], v[142:143], v[106:107] op_sel_hi:[0,1]
	v_pk_mul_f32 v[106:107], v[106:107], v[26:27]
	v_pk_mul_f32 v[106:107], v[106:107], v[122:123]
	v_cvt_pk_bf16_f32 v133, v106, v107
	v_pk_mul_f32 v[108:109], v[142:143], v[108:109] op_sel_hi:[0,1]
	v_pk_mul_f32 v[108:109], v[108:109], v[28:29]
	v_pk_mul_f32 v[108:109], v[108:109], v[124:125]
	v_cvt_pk_bf16_f32 v134, v108, v109
	v_pk_mul_f32 v[110:111], v[142:143], v[110:111] op_sel_hi:[0,1]
	v_pk_mul_f32 v[110:111], v[110:111], v[30:31]
	v_pk_mul_f32 v[110:111], v[110:111], v[126:127]
	v_cvt_pk_bf16_f32 v135, v110, v111
	global_store_dwordx4 v2, v[128:131], s[24:25]
	global_store_dwordx4 v2, v[132:135], s[24:25] offset:16
	s_cmp_eq_u32 s22, 0
	s_cbranch_scc1 .Lma_done
	s_mov_b32 s3, s23
	s_branch .Lma_half_A
.Lma_done:
	s_mov_b64 s[4:5], exec
.LBB0_511:
	s_or_b64 exec, exec, s[4:5]
	s_cmpk_gt_i32 s2, 0xfff
	s_cbranch_scc1 .LBB0_526
	s_waitcnt lgkmcnt(0)
	v_and_b32_e32 v1, 0x3ff, v0
	v_lshrrev_b32_e32 v2, 3, v1
	v_and_b32_e32 v3, 7, v1
	v_mul_u32_u24_e32 v4, 0x41, v2
	v_lshl_add_u32 v4, v3, 3, v4
	v_lshlrev_b32_e32 v4, 3, v4
	v_mul_u32_u24_e32 v5, 0x208, v3
	v_add_u32_e32 v5, v5, v2
	v_lshlrev_b32_e32 v5, 3, v5
	v_lshlrev_b32_e32 v6, 16, v2
	v_lshl_add_u32 v6, v3, 5, v6
	v_lshlrev_b32_e32 v8, 4, v3
	v_add_u32_e32 v7, -1, v2
	v_max_i32_e32 v7, 0, v7
	v_add_u32_e32 v9, 1, v2
	v_min_i32_e32 v9, 63, v9
	v_lshl_add_u32 v7, v7, 11, v8
	v_lshl_add_u32 v9, v9, 11, v8
	v_lshl_add_u32 v10, v2, 12, v8
	v_lshl_add_u32 v8, v2, 11, v8
	v_lshlrev_b32_e32 v13, 5, v3
	v_cmp_lt_u32_e32 vcc, 0, v2
	s_nop 1
	v_cndmask_b32_e64 v11, 0, 1.0, vcc
	v_cmp_gt_u32_e32 vcc, 63, v2
	s_nop 1
	v_cndmask_b32_e64 v12, 0, 1.0, vcc
	v_readlane_b32 s36, v254, 0
	v_readlane_b32 s37, v254, 1
	v_readlane_b32 s38, v254, 2
	v_readlane_b32 s39, v254, 3
	s_mov_b32 s3, s2
	s_mov_b32 s5, -1
	s_mov_b32 s28, 0
	s_lshr_b32 s6, s3, 4
	s_and_b32 s7, s3, 15
	s_lshl_b32 s10, s7, 22
	s_lshl_b32 s11, s6, 8
	s_add_u32 s10, s10, s11
	s_add_u32 s12, s84, s10
	s_addc_u32 s13, s85, 0
	s_add_u32 s12, s12, 0x33d00000
	s_addc_u32 s13, s13, 0
	s_add_u32 s14, s12, 0x4000000
	s_addc_u32 s15, s13, 0
	s_lshl_b32 s10, s6, 17
	s_lshl_b32 s11, s7, 7
	s_add_u32 s10, s10, s11
	s_add_u32 s16, s84, s10
	s_addc_u32 s17, s85, 0
	s_add_u32 s16, s16, 0x1fd00000
	s_addc_u32 s17, s17, 0
	s_add_u32 s18, s16, 0x2000000
	s_addc_u32 s19, s17, 0
	global_load_dwordx4 v[48:51], v6, s[12:13]
	global_load_dwordx4 v[52:55], v6, s[12:13] offset:16
	global_load_dwordx4 v[56:59], v6, s[14:15]
	global_load_dwordx4 v[60:63], v6, s[14:15] offset:16
	global_load_dwordx4 v[80:83], v7, s[16:17]
	global_load_dwordx4 v[84:87], v8, s[16:17]
	global_load_dwordx4 v[88:91], v9, s[16:17]
	global_load_dwordx4 v[92:95], v7, s[18:19]
	global_load_dwordx4 v[96:99], v8, s[18:19]
	global_load_dwordx4 v[100:103], v9, s[18:19]
